# LQ: QK^T K-fragment LDS reads in all attention tile loops issued together into spare registers (was a serial read-wait-MFMA chain); bit-identical
# speedup vs baseline: 1.0144x; 1.0144x over previous
.LBB0_667:
	s_cmp_gt_i32 s86, s15
	s_waitcnt lgkmcnt(0)
	s_barrier
	s_cbranch_scc1 .LBB0_674
	s_mulk_i32 s6, 0x4a00
	v_lshl_or_b32 v0, v141, 2, s6
	ds_read_b128 v[2:5], v0 offset:18528
	ds_read_b128 v[6:9], v0 offset:18496
	ds_read_b128 v[10:13], v0 offset:18464
	ds_read_b128 v[48:51], v0 offset:18432
	v_add3_u32 v14, s6, v144, v118
	s_waitcnt lgkmcnt(3)
	v_pk_add_f32 v[60:61], v[136:137], v[2:3] op_sel_hi:[0,1]
	v_pk_add_f32 v[62:63], v[136:137], v[4:5] op_sel_hi:[0,1]
	ds_read_b128 v[2:5], v14
	s_waitcnt lgkmcnt(3)
	v_pk_add_f32 v[56:57], v[136:137], v[6:7] op_sel_hi:[0,1]
	s_waitcnt lgkmcnt(2)
	v_pk_add_f32 v[52:53], v[136:137], v[10:11] op_sel_hi:[0,1]
	s_waitcnt lgkmcnt(1)
	v_pk_add_f32 v[48:49], v[136:137], v[48:49] op_sel_hi:[0,1]
	v_pk_add_f32 v[58:59], v[136:137], v[8:9] op_sel_hi:[0,1]
	v_pk_add_f32 v[54:55], v[136:137], v[12:13] op_sel_hi:[0,1]
	v_pk_add_f32 v[50:51], v[136:137], v[50:51] op_sel_hi:[0,1]
	ds_read_b128 v[6:9], v0 offset:18656
	ds_read_b128 v[10:13], v0 offset:18560
	ds_read_b128 v[64:67], v0 offset:18624
	ds_read_b128 v[68:71], v0 offset:18592
	ds_read_b128 v[150:153], v14 offset:4608
	s_waitcnt lgkmcnt(5)
	v_mfma_f32_32x32x16_bf16 v[48:63], v[2:5], v[80:83], v[48:63]
	ds_read_b128 v[2:5], v14 offset:32
	ds_read_b128 v[236:239], v14 offset:4640
	ds_read_b128 v[240:243], v14 offset:64
	ds_read_b128 v[244:247], v14 offset:4672
	ds_read_b128 v[248:251], v14 offset:96
	s_waitcnt lgkmcnt(9)
	v_add_f32_e64 v76, v136, v6
	v_add_f32_e64 v77, v136, v7
	s_waitcnt lgkmcnt(7)
	v_pk_add_f32 v[72:73], v[136:137], v[64:65] op_sel_hi:[0,1]
	s_waitcnt lgkmcnt(6)
	v_pk_add_f32 v[68:69], v[136:137], v[68:69] op_sel_hi:[0,1]
	v_pk_add_f32 v[64:65], v[136:137], v[10:11] op_sel_hi:[0,1]
	v_pk_add_f32 v[78:79], v[136:137], v[8:9] op_sel_hi:[0,1]
	v_pk_add_f32 v[74:75], v[136:137], v[66:67] op_sel_hi:[0,1]
	v_pk_add_f32 v[70:71], v[136:137], v[70:71] op_sel_hi:[0,1]
	v_pk_add_f32 v[66:67], v[136:137], v[12:13] op_sel_hi:[0,1]
	s_waitcnt lgkmcnt(4)
	v_mfma_f32_32x32x16_bf16 v[48:63], v[2:5], v[84:87], v[48:63]
	ds_read_b128 v[2:5], v14 offset:4704
	s_add_i32 s0, s86, 63
	v_cmp_le_i32_e32 vcc, s0, v116
	s_cmp_eq_u64 vcc, exec
	v_mfma_f32_32x32x16_bf16 v[64:79], v[150:153], v[80:83], v[64:79]
	s_waitcnt lgkmcnt(4)
	v_mfma_f32_32x32x16_bf16 v[64:79], v[236:239], v[84:87], v[64:79]
	s_waitcnt lgkmcnt(3)
	v_mfma_f32_32x32x16_bf16 v[48:63], v[240:243], v[88:91], v[48:63]
	s_waitcnt lgkmcnt(2)
	v_mfma_f32_32x32x16_bf16 v[64:79], v[244:247], v[88:91], v[64:79]
	s_waitcnt lgkmcnt(1)
	v_mfma_f32_32x32x16_bf16 v[48:63], v[248:251], v[92:95], v[48:63]
	s_waitcnt lgkmcnt(0)
	v_mfma_f32_32x32x16_bf16 v[64:79], v[2:5], v[92:95], v[64:79]
	s_cbranch_scc1 .LBB0_672
	v_add_u32_e32 v0, s86, v141
	v_cmp_lt_i32_e32 vcc, v0, v116
	v_add_u32_e32 v2, 2, v0
	s_nop 4
	v_cndmask_b32_e32 v49, v169, v49, vcc
	v_cmp_le_i32_e32 vcc, v0, v116
	s_nop 1
	v_cndmask_b32_e32 v48, v169, v48, vcc
	v_cmp_le_i32_e32 vcc, v2, v116
	v_add_u32_e32 v2, 3, v0
	s_nop 0
	v_cndmask_b32_e32 v50, v169, v50, vcc
	v_cmp_le_i32_e32 vcc, v2, v116
	v_add_u32_e32 v2, 8, v0
	s_nop 0
	v_cndmask_b32_e32 v51, v169, v51, vcc
	v_cmp_le_i32_e32 vcc, v2, v116
	v_add_u32_e32 v2, 9, v0
	s_nop 0
	v_cndmask_b32_e32 v52, v169, v52, vcc
	v_cmp_le_i32_e32 vcc, v2, v116
	v_add_u32_e32 v2, 10, v0
	s_nop 0
	v_cndmask_b32_e32 v53, v169, v53, vcc
	v_cmp_le_i32_e32 vcc, v2, v116
	v_add_u32_e32 v2, 11, v0
	s_nop 0
	v_cndmask_b32_e32 v54, v169, v54, vcc
	v_cmp_le_i32_e32 vcc, v2, v116
	v_add_u32_e32 v2, 16, v0
	s_nop 0
	v_cndmask_b32_e32 v55, v169, v55, vcc
	v_cmp_le_i32_e32 vcc, v2, v116
	v_add_u32_e32 v2, 17, v0
	s_nop 0
	v_cndmask_b32_e32 v56, v169, v56, vcc
	v_cmp_le_i32_e32 vcc, v2, v116
	v_add_u32_e32 v2, 18, v0
	s_nop 0
	v_cndmask_b32_e32 v57, v169, v57, vcc
	v_cmp_le_i32_e32 vcc, v2, v116
	v_add_u32_e32 v2, 19, v0
	s_nop 0
	v_cndmask_b32_e32 v58, v169, v58, vcc
	v_cmp_le_i32_e32 vcc, v2, v116
	v_add_u32_e32 v2, 24, v0
	s_nop 0
	v_cndmask_b32_e32 v59, v169, v59, vcc
	v_cmp_le_i32_e32 vcc, v2, v116
	v_add_u32_e32 v2, 25, v0
	s_nop 0
	v_cndmask_b32_e32 v60, v169, v60, vcc
	v_cmp_le_i32_e32 vcc, v2, v116
	v_add_u32_e32 v2, 26, v0
	s_nop 0
	v_cndmask_b32_e32 v61, v169, v61, vcc
	v_cmp_le_i32_e32 vcc, v2, v116
	v_add_u32_e32 v2, 27, v0
	s_nop 0
	v_cndmask_b32_e32 v62, v169, v62, vcc
	v_cmp_le_i32_e32 vcc, v2, v116
	v_add_u32_e32 v2, 32, v0
	s_nop 0
	v_cndmask_b32_e32 v63, v169, v63, vcc
	v_cmp_le_i32_e32 vcc, v2, v116
	v_add_u32_e32 v2, 33, v0
	s_nop 0
	v_cndmask_b32_e32 v64, v169, v64, vcc
	v_cmp_le_i32_e32 vcc, v2, v116
	v_add_u32_e32 v2, 34, v0
	s_nop 0
	v_cndmask_b32_e32 v65, v169, v65, vcc
	v_cmp_le_i32_e32 vcc, v2, v116
	v_add_u32_e32 v2, 35, v0
	s_nop 0
	v_cndmask_b32_e32 v66, v169, v66, vcc
	v_cmp_le_i32_e32 vcc, v2, v116
	v_add_u32_e32 v2, 40, v0
	s_nop 0
	v_cndmask_b32_e32 v67, v169, v67, vcc
	v_cmp_le_i32_e32 vcc, v2, v116
	v_add_u32_e32 v2, 41, v0
	s_nop 0
	v_cndmask_b32_e32 v68, v169, v68, vcc
	v_cmp_le_i32_e32 vcc, v2, v116
	v_add_u32_e32 v2, 42, v0
	s_nop 0
	v_cndmask_b32_e32 v69, v169, v69, vcc
	v_cmp_le_i32_e32 vcc, v2, v116
	v_add_u32_e32 v2, 43, v0
	s_nop 0
	v_cndmask_b32_e32 v70, v169, v70, vcc
	v_cmp_le_i32_e32 vcc, v2, v116
	v_add_u32_e32 v2, 48, v0
	s_nop 0
	v_cndmask_b32_e32 v71, v169, v71, vcc
	v_cmp_le_i32_e32 vcc, v2, v116
	v_add_u32_e32 v2, 49, v0
	s_nop 0
	v_cndmask_b32_e32 v72, v169, v72, vcc
	v_cmp_le_i32_e32 vcc, v2, v116
	v_add_u32_e32 v2, 50, v0
	s_nop 0
	v_cndmask_b32_e32 v73, v169, v73, vcc
	v_cmp_le_i32_e32 vcc, v2, v116
	v_add_u32_e32 v2, 51, v0
	s_nop 0
	v_cndmask_b32_e32 v74, v169, v74, vcc
	v_cmp_le_i32_e32 vcc, v2, v116
	v_add_u32_e32 v2, 56, v0
	s_nop 0
	v_cndmask_b32_e32 v75, v169, v75, vcc
	v_cmp_le_i32_e32 vcc, v2, v116
	v_add_u32_e32 v2, 57, v0
	s_nop 0
	v_cndmask_b32_e32 v76, v169, v76, vcc
	v_cmp_le_i32_e32 vcc, v2, v116
	v_add_u32_e32 v2, 58, v0
	v_add_u32_e32 v0, 59, v0
	v_cndmask_b32_e32 v77, v169, v77, vcc
	v_cmp_le_i32_e32 vcc, v2, v116
	s_nop 1
	v_cndmask_b32_e32 v78, v169, v78, vcc
	v_cmp_gt_i32_e32 vcc, v0, v116
	s_and_saveexec_b64 s[0:1], vcc
	v_mov_b32_e32 v79, 0xf149f2ca
	s_or_b64 exec, exec, s[0:1]

.LBB0_700:
	s_cmp_gt_i32 s7, s5
	s_waitcnt lgkmcnt(0)
	s_barrier
	s_cbranch_scc1 .LBB0_707
	s_mul_i32 s14, s0, 0x4a00
	v_add_u32_e32 v0, s14, v148
	v_add3_u32 v0, v0, v130, v132
	ds_read_b128 v[2:5], v0
	ds_read_b128 v[236:239], v0 offset:4608
	ds_read_b128 v[240:243], v0 offset:32
	ds_read_b128 v[244:247], v0 offset:4640
	s_add_i32 s0, s7, 63
	v_cmp_le_i32_e32 vcc, s0, v128
	s_cmp_eq_u64 vcc, exec
	s_waitcnt lgkmcnt(3)
	v_mfma_f32_32x32x16_bf16 v[80:95], v[2:5], v[96:99], v[48:63]
	s_waitcnt lgkmcnt(2)
	v_mfma_f32_32x32x16_bf16 v[64:79], v[236:239], v[96:99], v[48:63]
	s_waitcnt lgkmcnt(1)
	v_mfma_f32_32x32x16_bf16 v[80:95], v[240:243], v[100:103], v[80:95]
	s_waitcnt lgkmcnt(0)
	v_mfma_f32_32x32x16_bf16 v[64:79], v[244:247], v[100:103], v[64:79]
	s_cbranch_scc1 .LBB0_705
	v_add_u32_e32 v0, s7, v125
	v_cmp_lt_i32_e32 vcc, v0, v128
	v_add_u32_e32 v2, 2, v0
	s_nop 4
	v_cndmask_b32_e32 v81, v169, v81, vcc
	v_cmp_le_i32_e32 vcc, v0, v128
	s_nop 1
	v_cndmask_b32_e32 v80, v169, v80, vcc
	v_cmp_le_i32_e32 vcc, v2, v128
	v_add_u32_e32 v2, 3, v0
	s_nop 0
	v_cndmask_b32_e32 v82, v169, v82, vcc
	v_cmp_le_i32_e32 vcc, v2, v128
	v_add_u32_e32 v2, 8, v0
	s_nop 0
	v_cndmask_b32_e32 v83, v169, v83, vcc
	v_cmp_le_i32_e32 vcc, v2, v128
	v_add_u32_e32 v2, 9, v0
	s_nop 0
	v_cndmask_b32_e32 v84, v169, v84, vcc
	v_cmp_le_i32_e32 vcc, v2, v128
	v_add_u32_e32 v2, 10, v0
	s_nop 0
	v_cndmask_b32_e32 v85, v169, v85, vcc
	v_cmp_le_i32_e32 vcc, v2, v128
	v_add_u32_e32 v2, 11, v0
	s_nop 0
	v_cndmask_b32_e32 v86, v169, v86, vcc
	v_cmp_le_i32_e32 vcc, v2, v128
	v_add_u32_e32 v2, 16, v0
	s_nop 0
	v_cndmask_b32_e32 v87, v169, v87, vcc
	v_cmp_le_i32_e32 vcc, v2, v128
	v_add_u32_e32 v2, 17, v0
	s_nop 0
	v_cndmask_b32_e32 v88, v169, v88, vcc
	v_cmp_le_i32_e32 vcc, v2, v128
	v_add_u32_e32 v2, 18, v0
	s_nop 0
	v_cndmask_b32_e32 v89, v169, v89, vcc
	v_cmp_le_i32_e32 vcc, v2, v128
	v_add_u32_e32 v2, 19, v0
	s_nop 0
	v_cndmask_b32_e32 v90, v169, v90, vcc
	v_cmp_le_i32_e32 vcc, v2, v128
	v_add_u32_e32 v2, 24, v0
	s_nop 0
	v_cndmask_b32_e32 v91, v169, v91, vcc
	v_cmp_le_i32_e32 vcc, v2, v128
	v_add_u32_e32 v2, 25, v0
	s_nop 0
	v_cndmask_b32_e32 v92, v169, v92, vcc
	v_cmp_le_i32_e32 vcc, v2, v128
	v_add_u32_e32 v2, 26, v0
	s_nop 0
	v_cndmask_b32_e32 v93, v169, v93, vcc
	v_cmp_le_i32_e32 vcc, v2, v128
	v_add_u32_e32 v2, 27, v0
	s_nop 0
	v_cndmask_b32_e32 v94, v169, v94, vcc
	v_cmp_le_i32_e32 vcc, v2, v128
	v_add_u32_e32 v2, 32, v0
	s_nop 0
	v_cndmask_b32_e32 v95, v169, v95, vcc
	v_cmp_le_i32_e32 vcc, v2, v128
	v_add_u32_e32 v2, 33, v0
	s_nop 0
	v_cndmask_b32_e32 v64, v169, v64, vcc
	v_cmp_le_i32_e32 vcc, v2, v128
	v_add_u32_e32 v2, 34, v0
	s_nop 0
	v_cndmask_b32_e32 v65, v169, v65, vcc
	v_cmp_le_i32_e32 vcc, v2, v128
	v_add_u32_e32 v2, 35, v0
	s_nop 0
	v_cndmask_b32_e32 v66, v169, v66, vcc
	v_cmp_le_i32_e32 vcc, v2, v128
	v_add_u32_e32 v2, 40, v0
	s_nop 0
	v_cndmask_b32_e32 v67, v169, v67, vcc
	v_cmp_le_i32_e32 vcc, v2, v128
	v_add_u32_e32 v2, 41, v0
	s_nop 0
	v_cndmask_b32_e32 v68, v169, v68, vcc
	v_cmp_le_i32_e32 vcc, v2, v128
	v_add_u32_e32 v2, 42, v0
	s_nop 0
	v_cndmask_b32_e32 v69, v169, v69, vcc
	v_cmp_le_i32_e32 vcc, v2, v128
	v_add_u32_e32 v2, 43, v0
	s_nop 0
	v_cndmask_b32_e32 v70, v169, v70, vcc
	v_cmp_le_i32_e32 vcc, v2, v128
	v_add_u32_e32 v2, 48, v0
	s_nop 0
	v_cndmask_b32_e32 v71, v169, v71, vcc
	v_cmp_le_i32_e32 vcc, v2, v128
	v_add_u32_e32 v2, 49, v0
	s_nop 0
	v_cndmask_b32_e32 v72, v169, v72, vcc
	v_cmp_le_i32_e32 vcc, v2, v128
	v_add_u32_e32 v2, 50, v0
	s_nop 0
	v_cndmask_b32_e32 v73, v169, v73, vcc
	v_cmp_le_i32_e32 vcc, v2, v128
	v_add_u32_e32 v2, 51, v0
	s_nop 0
	v_cndmask_b32_e32 v74, v169, v74, vcc
	v_cmp_le_i32_e32 vcc, v2, v128
	v_add_u32_e32 v2, 56, v0
	s_nop 0
	v_cndmask_b32_e32 v75, v169, v75, vcc
	v_cmp_le_i32_e32 vcc, v2, v128
	v_add_u32_e32 v2, 57, v0
	s_nop 0
	v_cndmask_b32_e32 v76, v169, v76, vcc
	v_cmp_le_i32_e32 vcc, v2, v128
	v_add_u32_e32 v2, 58, v0
	v_add_u32_e32 v0, 59, v0
	v_cndmask_b32_e32 v77, v169, v77, vcc
	v_cmp_le_i32_e32 vcc, v2, v128
	s_nop 1
	v_cndmask_b32_e32 v78, v169, v78, vcc
	v_cmp_gt_i32_e32 vcc, v0, v128
	s_and_saveexec_b64 s[0:1], vcc
	v_mov_b32_e32 v79, 0xf149f2ca
	s_or_b64 exec, exec, s[0:1]

.LBB0_775:
	s_cmp_gt_i32 s17, s16
	s_waitcnt lgkmcnt(0)
	s_barrier
	s_cbranch_scc1 .LBB0_782
	s_mulk_i32 s4, 0x4a00
	v_add_u32_e32 v76, s4, v71
	ds_read_b128 v[18:21], v76
	ds_read_b128 v[72:75], v76 offset:4608
	ds_read_b128 v[236:239], v76 offset:32
	ds_read_b128 v[240:243], v76 offset:4640
	ds_read_b128 v[244:247], v76 offset:64
	ds_read_b128 v[248:251], v76 offset:4672
	s_add_i32 s4, s22, 63
	v_cmp_le_i32_e32 vcc, s4, v198
	s_cmp_eq_u64 vcc, exec
	s_waitcnt lgkmcnt(5)
	v_mfma_f32_32x32x16_bf16 v[34:49], v[18:21], v[82:85], v[2:17]
	s_waitcnt lgkmcnt(4)
	v_mfma_f32_32x32x16_bf16 v[18:33], v[72:75], v[82:85], v[2:17]
	ds_read_b128 v[72:75], v76 offset:96
	s_waitcnt lgkmcnt(4)
	v_mfma_f32_32x32x16_bf16 v[34:49], v[236:239], v[86:89], v[34:49]
	ds_read_b128 v[236:239], v76 offset:4704
	s_waitcnt lgkmcnt(4)
	v_mfma_f32_32x32x16_bf16 v[18:33], v[240:243], v[86:89], v[18:33]
	s_waitcnt lgkmcnt(3)
	v_mfma_f32_32x32x16_bf16 v[34:49], v[244:247], v[90:93], v[34:49]
	s_waitcnt lgkmcnt(2)
	v_mfma_f32_32x32x16_bf16 v[18:33], v[248:251], v[90:93], v[18:33]
	s_waitcnt lgkmcnt(1)
	v_mfma_f32_32x32x16_bf16 v[34:49], v[72:75], v[94:97], v[34:49]
	s_waitcnt lgkmcnt(0)
	v_mfma_f32_32x32x16_bf16 v[18:33], v[236:239], v[94:97], v[18:33]
	s_cbranch_scc1 .LBB0_780
	v_add_u32_e32 v72, s22, v125
	v_cmp_lt_i32_e32 vcc, v72, v198
	v_add_u32_e32 v73, 2, v72
	s_nop 4
	v_cndmask_b32_e32 v35, v169, v35, vcc
	v_cmp_le_i32_e32 vcc, v72, v198
	s_nop 1
	v_cndmask_b32_e32 v34, v169, v34, vcc
	v_cmp_le_i32_e32 vcc, v73, v198
	v_add_u32_e32 v73, 3, v72
	s_nop 0
	v_cndmask_b32_e32 v36, v169, v36, vcc
	v_cmp_le_i32_e32 vcc, v73, v198
	v_add_u32_e32 v73, 8, v72
	s_nop 0
	v_cndmask_b32_e32 v37, v169, v37, vcc
	v_cmp_le_i32_e32 vcc, v73, v198
	v_add_u32_e32 v73, 9, v72
	s_nop 0
	v_cndmask_b32_e32 v38, v169, v38, vcc
	v_cmp_le_i32_e32 vcc, v73, v198
	v_add_u32_e32 v73, 10, v72
	s_nop 0
	v_cndmask_b32_e32 v39, v169, v39, vcc
	v_cmp_le_i32_e32 vcc, v73, v198
	v_add_u32_e32 v73, 11, v72
	s_nop 0
	v_cndmask_b32_e32 v40, v169, v40, vcc
	v_cmp_le_i32_e32 vcc, v73, v198
	v_add_u32_e32 v73, 16, v72
	s_nop 0
	v_cndmask_b32_e32 v41, v169, v41, vcc
	v_cmp_le_i32_e32 vcc, v73, v198
	v_add_u32_e32 v73, 17, v72
	s_nop 0
	v_cndmask_b32_e32 v42, v169, v42, vcc
	v_cmp_le_i32_e32 vcc, v73, v198
	v_add_u32_e32 v73, 18, v72
	s_nop 0
	v_cndmask_b32_e32 v43, v169, v43, vcc
	v_cmp_le_i32_e32 vcc, v73, v198
	v_add_u32_e32 v73, 19, v72
	s_nop 0
	v_cndmask_b32_e32 v44, v169, v44, vcc
	v_cmp_le_i32_e32 vcc, v73, v198
	v_add_u32_e32 v73, 24, v72
	s_nop 0
	v_cndmask_b32_e32 v45, v169, v45, vcc
	v_cmp_le_i32_e32 vcc, v73, v198
	v_add_u32_e32 v73, 25, v72
	s_nop 0
	v_cndmask_b32_e32 v46, v169, v46, vcc
	v_cmp_le_i32_e32 vcc, v73, v198
	v_add_u32_e32 v73, 26, v72
	s_nop 0
	v_cndmask_b32_e32 v47, v169, v47, vcc
	v_cmp_le_i32_e32 vcc, v73, v198
	v_add_u32_e32 v73, 27, v72
	s_nop 0
	v_cndmask_b32_e32 v48, v169, v48, vcc
	v_cmp_le_i32_e32 vcc, v73, v198
	v_add_u32_e32 v73, 32, v72
	s_nop 0
	v_cndmask_b32_e32 v49, v169, v49, vcc
	v_cmp_le_i32_e32 vcc, v73, v198
	v_add_u32_e32 v73, 33, v72
	s_nop 0
	v_cndmask_b32_e32 v18, v169, v18, vcc
	v_cmp_le_i32_e32 vcc, v73, v198
	v_add_u32_e32 v73, 34, v72
	s_nop 0
	v_cndmask_b32_e32 v19, v169, v19, vcc
	v_cmp_le_i32_e32 vcc, v73, v198
	v_add_u32_e32 v73, 35, v72
	s_nop 0
	v_cndmask_b32_e32 v20, v169, v20, vcc
	v_cmp_le_i32_e32 vcc, v73, v198
	v_add_u32_e32 v73, 40, v72
	s_nop 0
	v_cndmask_b32_e32 v21, v169, v21, vcc
	v_cmp_le_i32_e32 vcc, v73, v198
	v_add_u32_e32 v73, 41, v72
	s_nop 0
	v_cndmask_b32_e32 v22, v169, v22, vcc
	v_cmp_le_i32_e32 vcc, v73, v198
	v_add_u32_e32 v73, 42, v72
	s_nop 0
	v_cndmask_b32_e32 v23, v169, v23, vcc
	v_cmp_le_i32_e32 vcc, v73, v198
	v_add_u32_e32 v73, 43, v72
	s_nop 0
	v_cndmask_b32_e32 v24, v169, v24, vcc
	v_cmp_le_i32_e32 vcc, v73, v198
	v_add_u32_e32 v73, 48, v72
	s_nop 0
	v_cndmask_b32_e32 v25, v169, v25, vcc
	v_cmp_le_i32_e32 vcc, v73, v198
	v_add_u32_e32 v73, 49, v72
	s_nop 0
	v_cndmask_b32_e32 v26, v169, v26, vcc
	v_cmp_le_i32_e32 vcc, v73, v198
	v_add_u32_e32 v73, 50, v72
	s_nop 0
	v_cndmask_b32_e32 v27, v169, v27, vcc
	v_cmp_le_i32_e32 vcc, v73, v198
	v_add_u32_e32 v73, 51, v72
	s_nop 0
	v_cndmask_b32_e32 v28, v169, v28, vcc
	v_cmp_le_i32_e32 vcc, v73, v198
	v_add_u32_e32 v73, 56, v72
	s_nop 0
	v_cndmask_b32_e32 v29, v169, v29, vcc
	v_cmp_le_i32_e32 vcc, v73, v198
	v_add_u32_e32 v73, 57, v72
	s_nop 0
	v_cndmask_b32_e32 v30, v169, v30, vcc
	v_cmp_le_i32_e32 vcc, v73, v198
	v_add_u32_e32 v73, 58, v72
	v_add_u32_e32 v72, 59, v72
	v_cndmask_b32_e32 v31, v169, v31, vcc
	v_cmp_le_i32_e32 vcc, v73, v198
	s_nop 1
	v_cndmask_b32_e32 v32, v169, v32, vcc
	v_cmp_gt_i32_e32 vcc, v72, v198
	s_and_saveexec_b64 s[4:5], vcc
	v_mov_b32_e32 v33, 0xf149f2ca
	s_or_b64 exec, exec, s[4:5]

.LBB0_792:
	s_cmp_gt_i32 s5, s4
	s_waitcnt lgkmcnt(0)
	s_barrier
	s_cbranch_scc1 .LBB0_800
	s_mul_i32 s17, s0, 0x4a00
	v_add3_u32 v152, s17, v182, v130
	ds_read_b128 v[50:53], v152
	ds_read_b128 v[148:151], v152 offset:4608
	ds_read_b128 v[236:239], v152 offset:32
	ds_read_b128 v[240:243], v152 offset:4640
	ds_read_b128 v[244:247], v152 offset:64
	ds_read_b128 v[248:251], v152 offset:4672
	s_add_i32 s0, s86, 0xffffffbf
	v_cmp_le_i32_e32 vcc, s0, v198
	s_cmp_eq_u64 vcc, exec
	s_waitcnt lgkmcnt(5)
	v_mfma_f32_32x32x16_bf16 v[66:81], v[50:53], v[82:85], v[34:49]
	s_waitcnt lgkmcnt(4)
	v_mfma_f32_32x32x16_bf16 v[50:65], v[148:151], v[82:85], v[34:49]
	ds_read_b128 v[148:151], v152 offset:96
	s_waitcnt lgkmcnt(4)
	v_mfma_f32_32x32x16_bf16 v[66:81], v[236:239], v[86:89], v[66:81]
	ds_read_b128 v[236:239], v152 offset:4704
	s_waitcnt lgkmcnt(4)
	v_mfma_f32_32x32x16_bf16 v[50:65], v[240:243], v[86:89], v[50:65]
	s_waitcnt lgkmcnt(3)
	v_mfma_f32_32x32x16_bf16 v[66:81], v[244:247], v[90:93], v[66:81]
	s_waitcnt lgkmcnt(2)
	v_mfma_f32_32x32x16_bf16 v[50:65], v[248:251], v[90:93], v[50:65]
	s_waitcnt lgkmcnt(1)
	v_mfma_f32_32x32x16_bf16 v[66:81], v[148:151], v[94:97], v[66:81]
	s_waitcnt lgkmcnt(0)
	v_mfma_f32_32x32x16_bf16 v[50:65], v[236:239], v[94:97], v[50:65]
	s_cbranch_scc1 .LBB0_797
	v_add_u32_e32 v148, s86, v125
	v_add_u32_e32 v149, 0xffffff80, v148
	v_cmp_lt_i32_e32 vcc, v149, v198
	s_nop 4
	v_cndmask_b32_e32 v67, v169, v67, vcc
	v_cmp_le_i32_e32 vcc, v149, v198
	v_add_u32_e32 v149, 0xffffff82, v148
	s_nop 0
	v_cndmask_b32_e32 v66, v169, v66, vcc
	v_cmp_le_i32_e32 vcc, v149, v198
	v_add_u32_e32 v149, 0xffffff83, v148
	s_nop 0
	v_cndmask_b32_e32 v68, v169, v68, vcc
	v_cmp_le_i32_e32 vcc, v149, v198
	v_add_u32_e32 v149, 0xffffff88, v148
	s_nop 0
	v_cndmask_b32_e32 v69, v169, v69, vcc
	v_cmp_le_i32_e32 vcc, v149, v198
	v_add_u32_e32 v149, 0xffffff89, v148
	s_nop 0
	v_cndmask_b32_e32 v70, v169, v70, vcc
	v_cmp_le_i32_e32 vcc, v149, v198
	v_add_u32_e32 v149, 0xffffff8a, v148
	s_nop 0
	v_cndmask_b32_e32 v71, v169, v71, vcc
	v_cmp_le_i32_e32 vcc, v149, v198
	v_add_u32_e32 v149, 0xffffff8b, v148
	s_nop 0
	v_cndmask_b32_e32 v72, v169, v72, vcc
	v_cmp_le_i32_e32 vcc, v149, v198
	v_add_u32_e32 v149, 0xffffff90, v148
	s_nop 0
	v_cndmask_b32_e32 v73, v169, v73, vcc
	v_cmp_le_i32_e32 vcc, v149, v198
	v_add_u32_e32 v149, 0xffffff91, v148
	s_nop 0
	v_cndmask_b32_e32 v74, v169, v74, vcc
	v_cmp_le_i32_e32 vcc, v149, v198
	v_add_u32_e32 v149, 0xffffff92, v148
	s_nop 0
	v_cndmask_b32_e32 v75, v169, v75, vcc
	v_cmp_le_i32_e32 vcc, v149, v198
	v_add_u32_e32 v149, 0xffffff93, v148
	s_nop 0
	v_cndmask_b32_e32 v76, v169, v76, vcc
	v_cmp_le_i32_e32 vcc, v149, v198
	v_add_u32_e32 v149, 0xffffff98, v148
	s_nop 0
	v_cndmask_b32_e32 v77, v169, v77, vcc
	v_cmp_le_i32_e32 vcc, v149, v198
	v_add_u32_e32 v149, 0xffffff99, v148
	s_nop 0
	v_cndmask_b32_e32 v78, v169, v78, vcc
	v_cmp_le_i32_e32 vcc, v149, v198
	v_add_u32_e32 v149, 0xffffff9a, v148
	s_nop 0
	v_cndmask_b32_e32 v79, v169, v79, vcc
	v_cmp_le_i32_e32 vcc, v149, v198
	v_add_u32_e32 v149, 0xffffff9b, v148
	s_nop 0
	v_cndmask_b32_e32 v80, v169, v80, vcc
	v_cmp_le_i32_e32 vcc, v149, v198
	v_add_u32_e32 v149, 0xffffffa0, v148
	s_nop 0
	v_cndmask_b32_e32 v81, v169, v81, vcc
	v_cmp_le_i32_e32 vcc, v149, v198
	v_add_u32_e32 v149, 0xffffffa1, v148
	s_nop 0
	v_cndmask_b32_e32 v50, v169, v50, vcc
	v_cmp_le_i32_e32 vcc, v149, v198
	v_add_u32_e32 v149, 0xffffffa2, v148
	s_nop 0
	v_cndmask_b32_e32 v51, v169, v51, vcc
	v_cmp_le_i32_e32 vcc, v149, v198
	v_add_u32_e32 v149, 0xffffffa3, v148
	s_nop 0
	v_cndmask_b32_e32 v52, v169, v52, vcc
	v_cmp_le_i32_e32 vcc, v149, v198
	v_add_u32_e32 v149, 0xffffffa8, v148
	s_nop 0
	v_cndmask_b32_e32 v53, v169, v53, vcc
	v_cmp_le_i32_e32 vcc, v149, v198
	v_add_u32_e32 v149, 0xffffffa9, v148
	s_nop 0
	v_cndmask_b32_e32 v54, v169, v54, vcc
	v_cmp_le_i32_e32 vcc, v149, v198
	v_add_u32_e32 v149, 0xffffffaa, v148
	s_nop 0
	v_cndmask_b32_e32 v55, v169, v55, vcc
	v_cmp_le_i32_e32 vcc, v149, v198
	v_add_u32_e32 v149, 0xffffffab, v148
	s_nop 0
	v_cndmask_b32_e32 v56, v169, v56, vcc
	v_cmp_le_i32_e32 vcc, v149, v198
	v_add_u32_e32 v149, 0xffffffb0, v148
	s_nop 0
	v_cndmask_b32_e32 v57, v169, v57, vcc
	v_cmp_le_i32_e32 vcc, v149, v198
	v_add_u32_e32 v149, 0xffffffb1, v148
	s_nop 0
	v_cndmask_b32_e32 v58, v169, v58, vcc
	v_cmp_le_i32_e32 vcc, v149, v198
	v_add_u32_e32 v149, 0xffffffb2, v148
	s_nop 0
	v_cndmask_b32_e32 v59, v169, v59, vcc
	v_cmp_le_i32_e32 vcc, v149, v198
	v_add_u32_e32 v149, 0xffffffb3, v148
	s_nop 0
	v_cndmask_b32_e32 v60, v169, v60, vcc
	v_cmp_le_i32_e32 vcc, v149, v198
	v_add_u32_e32 v149, 0xffffffb8, v148
	s_nop 0
	v_cndmask_b32_e32 v61, v169, v61, vcc
	v_cmp_le_i32_e32 vcc, v149, v198
	v_add_u32_e32 v149, 0xffffffb9, v148
	s_nop 0
	v_cndmask_b32_e32 v62, v169, v62, vcc
	v_cmp_le_i32_e32 vcc, v149, v198
	v_add_u32_e32 v149, 0xffffffba, v148
	v_add_u32_e32 v148, 0xffffffbb, v148
	v_cndmask_b32_e32 v63, v169, v63, vcc
	v_cmp_le_i32_e32 vcc, v149, v198
	s_nop 1
	v_cndmask_b32_e32 v64, v169, v64, vcc
	v_cmp_gt_i32_e32 vcc, v148, v198
	s_and_saveexec_b64 s[0:1], vcc
	v_mov_b32_e32 v65, 0xf149f2ca
	s_or_b64 exec, exec, s[0:1]

.LBB0_909:
	s_cmp_gt_i32 s15, s14
	s_waitcnt lgkmcnt(0)
	s_barrier
	s_cbranch_scc1 .LBB0_921
	s_lshr_b32 s1, s16, 3
	s_and_b32 s1, s1, 0x1ffffffc
	v_add_u32_e32 v50, s1, v114
	ds_read_b32 v50, v50
	s_and_b32 s1, s16, 31
	s_waitcnt lgkmcnt(0)
	v_bfe_u32 v51, v50, s1, 1
	v_cmp_ne_u32_e32 vcc, 0, v51
	s_cbranch_vccz .LBB0_921
	s_mul_i32 s22, s0, 0x4a00
	v_add3_u32 v193, s22, v182, v130
	v_lshrrev_b32_e32 v147, s1, v50
	ds_read_b128 v[148:151], v193 offset:4608
	ds_read_b128 v[50:53], v193
	ds_read_b128 v[152:155], v193 offset:32
	ds_read_b128 v[236:239], v193 offset:4640
	ds_read_b128 v[240:243], v193 offset:64
	ds_read_b128 v[244:247], v193 offset:4672
	ds_read_b128 v[248:251], v193 offset:96
	s_add_i32 s23, s15, 63
	v_cmp_le_i32_e32 vcc, s23, v128
	s_waitcnt lgkmcnt(5)
	v_mfma_f32_32x32x16_bf16 v[66:81], v[50:53], v[82:85], v[34:49]
	s_waitcnt lgkmcnt(4)
	v_mfma_f32_32x32x16_bf16 v[66:81], v[152:155], v[86:89], v[66:81]
	ds_read_b128 v[152:155], v193 offset:4704
	v_and_b32_e32 v147, 1, v147
	s_cmp_lg_u64 vcc, exec
	s_mov_b64 s[0:1], -1
	v_cmp_eq_u32_e32 vcc, 1, v147
	s_mov_b64 s[4:5], -1
	v_mfma_f32_32x32x16_bf16 v[50:65], v[148:151], v[82:85], v[34:49]
	s_waitcnt lgkmcnt(4)
	v_mfma_f32_32x32x16_bf16 v[50:65], v[236:239], v[86:89], v[50:65]
	s_waitcnt lgkmcnt(3)
	v_mfma_f32_32x32x16_bf16 v[66:81], v[240:243], v[90:93], v[66:81]
	s_waitcnt lgkmcnt(2)
	v_mfma_f32_32x32x16_bf16 v[50:65], v[244:247], v[90:93], v[50:65]
	s_waitcnt lgkmcnt(1)
	v_mfma_f32_32x32x16_bf16 v[66:81], v[248:251], v[94:97], v[66:81]
	s_waitcnt lgkmcnt(0)
	v_mfma_f32_32x32x16_bf16 v[50:65], v[152:155], v[94:97], v[50:65]
	s_cbranch_scc0 .LBB0_917
	v_cndmask_b32_e32 v148, -1, v128, vcc
	v_cmp_le_i32_e32 vcc, s23, v148
	s_cmp_eq_u64 vcc, exec
	s_cbranch_scc1 .LBB0_916
	v_add_u32_e32 v149, s15, v125
	v_cmp_lt_i32_e32 vcc, v149, v148
	v_add_u32_e32 v150, 2, v149
	s_nop 2
	v_cndmask_b32_e32 v67, v169, v67, vcc
	v_cmp_le_i32_e32 vcc, v149, v148
	s_nop 1
	v_cndmask_b32_e32 v66, v169, v66, vcc
	v_cmp_le_i32_e32 vcc, v150, v148
	v_add_u32_e32 v150, 3, v149
	s_nop 0
	v_cndmask_b32_e32 v68, v169, v68, vcc
	v_cmp_le_i32_e32 vcc, v150, v148
	v_add_u32_e32 v150, 8, v149
	s_nop 0
	v_cndmask_b32_e32 v69, v169, v69, vcc
	v_cmp_le_i32_e32 vcc, v150, v148
	v_add_u32_e32 v150, 9, v149
	s_nop 0
	v_cndmask_b32_e32 v70, v169, v70, vcc
	v_cmp_le_i32_e32 vcc, v150, v148
	v_add_u32_e32 v150, 10, v149
	s_nop 0
	v_cndmask_b32_e32 v71, v169, v71, vcc
	v_cmp_le_i32_e32 vcc, v150, v148
	v_add_u32_e32 v150, 11, v149
	s_nop 0
	v_cndmask_b32_e32 v72, v169, v72, vcc
	v_cmp_le_i32_e32 vcc, v150, v148
	v_add_u32_e32 v150, 16, v149
	s_nop 0
	v_cndmask_b32_e32 v73, v169, v73, vcc
	v_cmp_le_i32_e32 vcc, v150, v148
	v_add_u32_e32 v150, 17, v149
	s_nop 0
	v_cndmask_b32_e32 v74, v169, v74, vcc
	v_cmp_le_i32_e32 vcc, v150, v148
	v_add_u32_e32 v150, 18, v149
	s_nop 0
	v_cndmask_b32_e32 v75, v169, v75, vcc
	v_cmp_le_i32_e32 vcc, v150, v148
	v_add_u32_e32 v150, 19, v149
	s_nop 0
	v_cndmask_b32_e32 v76, v169, v76, vcc
	v_cmp_le_i32_e32 vcc, v150, v148
	v_add_u32_e32 v150, 24, v149
	s_nop 0
	v_cndmask_b32_e32 v77, v169, v77, vcc
	v_cmp_le_i32_e32 vcc, v150, v148
	v_add_u32_e32 v150, 25, v149
	s_nop 0
	v_cndmask_b32_e32 v78, v169, v78, vcc
	v_cmp_le_i32_e32 vcc, v150, v148
	v_add_u32_e32 v150, 26, v149
	s_nop 0
	v_cndmask_b32_e32 v79, v169, v79, vcc
	v_cmp_le_i32_e32 vcc, v150, v148
	v_add_u32_e32 v150, 27, v149
	s_nop 0
	v_cndmask_b32_e32 v80, v169, v80, vcc
	v_cmp_le_i32_e32 vcc, v150, v148
	v_add_u32_e32 v150, 32, v149
	s_nop 0
	v_cndmask_b32_e32 v81, v169, v81, vcc
	v_cmp_le_i32_e32 vcc, v150, v148
	v_add_u32_e32 v150, 33, v149
	s_nop 0
	v_cndmask_b32_e32 v50, v169, v50, vcc
	v_cmp_le_i32_e32 vcc, v150, v148
	v_add_u32_e32 v150, 34, v149
	s_nop 0
	v_cndmask_b32_e32 v51, v169, v51, vcc
	v_cmp_le_i32_e32 vcc, v150, v148
	v_add_u32_e32 v150, 35, v149
	s_nop 0
	v_cndmask_b32_e32 v52, v169, v52, vcc
	v_cmp_le_i32_e32 vcc, v150, v148
	v_add_u32_e32 v150, 40, v149
	s_nop 0
	v_cndmask_b32_e32 v53, v169, v53, vcc
	v_cmp_le_i32_e32 vcc, v150, v148
	v_add_u32_e32 v150, 41, v149
	s_nop 0
	v_cndmask_b32_e32 v54, v169, v54, vcc
	v_cmp_le_i32_e32 vcc, v150, v148
	v_add_u32_e32 v150, 42, v149
	s_nop 0
	v_cndmask_b32_e32 v55, v169, v55, vcc
	v_cmp_le_i32_e32 vcc, v150, v148
	v_add_u32_e32 v150, 43, v149
	s_nop 0
	v_cndmask_b32_e32 v56, v169, v56, vcc
	v_cmp_le_i32_e32 vcc, v150, v148
	v_add_u32_e32 v150, 48, v149
	s_nop 0
	v_cndmask_b32_e32 v57, v169, v57, vcc
	v_cmp_le_i32_e32 vcc, v150, v148
	v_add_u32_e32 v150, 49, v149
	s_nop 0
	v_cndmask_b32_e32 v58, v169, v58, vcc
	v_cmp_le_i32_e32 vcc, v150, v148
	v_add_u32_e32 v150, 50, v149
	s_nop 0
	v_cndmask_b32_e32 v59, v169, v59, vcc
	v_cmp_le_i32_e32 vcc, v150, v148
	v_add_u32_e32 v150, 51, v149
	s_nop 0
	v_cndmask_b32_e32 v60, v169, v60, vcc
	v_cmp_le_i32_e32 vcc, v150, v148
	v_add_u32_e32 v150, 56, v149
	s_nop 0
	v_cndmask_b32_e32 v61, v169, v61, vcc
	v_cmp_le_i32_e32 vcc, v150, v148
	v_add_u32_e32 v150, 57, v149
	s_nop 0
	v_cndmask_b32_e32 v62, v169, v62, vcc
	v_cmp_le_i32_e32 vcc, v150, v148
	v_add_u32_e32 v150, 58, v149
	v_add_u32_e32 v149, 59, v149
	v_cndmask_b32_e32 v63, v169, v63, vcc
	v_cmp_le_i32_e32 vcc, v150, v148
	s_nop 1
	v_cndmask_b32_e32 v64, v169, v64, vcc
	v_cmp_gt_i32_e32 vcc, v149, v148
	s_and_saveexec_b64 s[4:5], vcc
	v_mov_b32_e32 v65, 0xf149f2ca
	s_or_b64 exec, exec, s[4:5]

.LBB0_931:
	s_cmp_le_i32 s14, s7
	s_cselect_b64 s[16:17], -1, 0
	s_add_i32 s1, s14, 63
	s_cmp_ge_i32 s1, s9
	s_cselect_b64 s[22:23], -1, 0
	s_and_b64 s[16:17], s[16:17], s[22:23]
	s_andn2_b64 vcc, exec, s[16:17]
	s_waitcnt lgkmcnt(0)
	s_barrier
	s_cbranch_vccnz .LBB0_938
	s_mul_i32 s16, s0, 0x4a00
	v_add3_u32 v142, s16, v182, v130
	ds_read_b128 v[50:53], v142
	ds_read_b128 v[138:141], v142 offset:4608
	ds_read_b128 v[236:239], v142 offset:32
	ds_read_b128 v[240:243], v142 offset:4640
	ds_read_b128 v[244:247], v142 offset:64
	ds_read_b128 v[248:251], v142 offset:4672
	v_cmp_le_i32_e32 vcc, s1, v128
	v_cmp_ge_i32_e64 s[0:1], s14, v137
	s_and_b64 s[0:1], vcc, s[0:1]
	s_waitcnt lgkmcnt(5)
	v_mfma_f32_32x32x16_bf16 v[66:81], v[50:53], v[82:85], v[34:49]
	s_waitcnt lgkmcnt(4)
	v_mfma_f32_32x32x16_bf16 v[50:65], v[138:141], v[82:85], v[34:49]
	ds_read_b128 v[138:141], v142 offset:96
	s_waitcnt lgkmcnt(4)
	v_mfma_f32_32x32x16_bf16 v[66:81], v[236:239], v[86:89], v[66:81]
	ds_read_b128 v[236:239], v142 offset:4704
	s_waitcnt lgkmcnt(4)
	v_mfma_f32_32x32x16_bf16 v[50:65], v[240:243], v[86:89], v[50:65]
	s_waitcnt lgkmcnt(3)
	v_mfma_f32_32x32x16_bf16 v[66:81], v[244:247], v[90:93], v[66:81]
	s_waitcnt lgkmcnt(2)
	v_mfma_f32_32x32x16_bf16 v[50:65], v[248:251], v[90:93], v[50:65]
	s_waitcnt lgkmcnt(1)
	v_mfma_f32_32x32x16_bf16 v[66:81], v[138:141], v[94:97], v[66:81]
	v_cndmask_b32_e64 v142, 0, 1, s[0:1]
	v_cmp_ne_u32_e32 vcc, 0, v142
	s_cmp_eq_u64 vcc, exec
	s_waitcnt lgkmcnt(0)
	v_mfma_f32_32x32x16_bf16 v[50:65], v[236:239], v[94:97], v[50:65]
	s_cbranch_scc1 .LBB0_936
	v_add_u32_e32 v138, s14, v125
	v_cmp_gt_i32_e32 vcc, v138, v128
	v_cmp_lt_i32_e64 s[0:1], v138, v137
	s_or_b64 vcc, vcc, s[0:1]
	v_add_u32_e32 v139, 1, v138
	v_cndmask_b32_e32 v66, v66, v169, vcc
	v_cmp_ge_i32_e32 vcc, v138, v128
	v_cmp_lt_i32_e64 s[0:1], v139, v137
	s_or_b64 vcc, vcc, s[0:1]
	v_add_u32_e32 v139, 2, v138
	v_cndmask_b32_e32 v67, v67, v169, vcc
	v_cmp_gt_i32_e32 vcc, v139, v128
	v_cmp_lt_i32_e64 s[0:1], v139, v137
	s_or_b64 vcc, vcc, s[0:1]
	v_add_u32_e32 v139, 3, v138
	v_cndmask_b32_e32 v68, v68, v169, vcc
	v_cmp_gt_i32_e32 vcc, v139, v128
	v_cmp_lt_i32_e64 s[0:1], v139, v137
	s_or_b64 vcc, vcc, s[0:1]
	v_add_u32_e32 v139, 8, v138
	v_cndmask_b32_e32 v69, v69, v169, vcc
	v_cmp_gt_i32_e32 vcc, v139, v128
	v_cmp_lt_i32_e64 s[0:1], v139, v137
	s_or_b64 vcc, vcc, s[0:1]
	v_add_u32_e32 v139, 9, v138
	v_cndmask_b32_e32 v70, v70, v169, vcc
	v_cmp_gt_i32_e32 vcc, v139, v128
	v_cmp_lt_i32_e64 s[0:1], v139, v137
	s_or_b64 vcc, vcc, s[0:1]
	v_add_u32_e32 v139, 10, v138
	v_cndmask_b32_e32 v71, v71, v169, vcc
	v_cmp_gt_i32_e32 vcc, v139, v128
	v_cmp_lt_i32_e64 s[0:1], v139, v137
	s_or_b64 vcc, vcc, s[0:1]
	v_add_u32_e32 v139, 11, v138
	v_cndmask_b32_e32 v72, v72, v169, vcc
	v_cmp_gt_i32_e32 vcc, v139, v128
	v_cmp_lt_i32_e64 s[0:1], v139, v137
	s_or_b64 vcc, vcc, s[0:1]
	v_add_u32_e32 v139, 16, v138
	v_cndmask_b32_e32 v73, v73, v169, vcc
	v_cmp_gt_i32_e32 vcc, v139, v128
	v_cmp_lt_i32_e64 s[0:1], v139, v137
	s_or_b64 vcc, vcc, s[0:1]
	v_add_u32_e32 v139, 17, v138
	v_cndmask_b32_e32 v74, v74, v169, vcc
	v_cmp_gt_i32_e32 vcc, v139, v128
	v_cmp_lt_i32_e64 s[0:1], v139, v137
	s_or_b64 vcc, vcc, s[0:1]
	v_add_u32_e32 v139, 18, v138
	v_cndmask_b32_e32 v75, v75, v169, vcc
	v_cmp_gt_i32_e32 vcc, v139, v128
	v_cmp_lt_i32_e64 s[0:1], v139, v137
	s_or_b64 vcc, vcc, s[0:1]
	v_add_u32_e32 v139, 19, v138
	v_cndmask_b32_e32 v76, v76, v169, vcc
	v_cmp_gt_i32_e32 vcc, v139, v128
	v_cmp_lt_i32_e64 s[0:1], v139, v137
	s_or_b64 vcc, vcc, s[0:1]
	v_add_u32_e32 v139, 24, v138
	v_cndmask_b32_e32 v77, v77, v169, vcc
	v_cmp_gt_i32_e32 vcc, v139, v128
	v_cmp_lt_i32_e64 s[0:1], v139, v137
	s_or_b64 vcc, vcc, s[0:1]
	v_add_u32_e32 v139, 25, v138
	v_cndmask_b32_e32 v78, v78, v169, vcc
	v_cmp_gt_i32_e32 vcc, v139, v128
	v_cmp_lt_i32_e64 s[0:1], v139, v137
	s_or_b64 vcc, vcc, s[0:1]
	v_add_u32_e32 v139, 26, v138
	v_cndmask_b32_e32 v79, v79, v169, vcc
	v_cmp_gt_i32_e32 vcc, v139, v128
	v_cmp_lt_i32_e64 s[0:1], v139, v137
	s_or_b64 vcc, vcc, s[0:1]
	v_add_u32_e32 v139, 27, v138
	v_cndmask_b32_e32 v80, v80, v169, vcc
	v_cmp_gt_i32_e32 vcc, v139, v128
	v_cmp_lt_i32_e64 s[0:1], v139, v137
	s_or_b64 vcc, vcc, s[0:1]
	v_add_u32_e32 v139, 32, v138
	v_cndmask_b32_e32 v81, v81, v169, vcc
	v_cmp_gt_i32_e32 vcc, v139, v128
	v_cmp_lt_i32_e64 s[0:1], v139, v137
	s_or_b64 vcc, vcc, s[0:1]
	v_add_u32_e32 v139, 33, v138
	v_cndmask_b32_e32 v50, v50, v169, vcc
	v_cmp_gt_i32_e32 vcc, v139, v128
	v_cmp_lt_i32_e64 s[0:1], v139, v137
	s_or_b64 vcc, vcc, s[0:1]
	v_add_u32_e32 v139, 34, v138
	v_cndmask_b32_e32 v51, v51, v169, vcc
	v_cmp_gt_i32_e32 vcc, v139, v128
	v_cmp_lt_i32_e64 s[0:1], v139, v137
	s_or_b64 vcc, vcc, s[0:1]
	v_add_u32_e32 v139, 35, v138
	v_cndmask_b32_e32 v52, v52, v169, vcc
	v_cmp_gt_i32_e32 vcc, v139, v128
	v_cmp_lt_i32_e64 s[0:1], v139, v137
	s_or_b64 vcc, vcc, s[0:1]
	v_add_u32_e32 v139, 40, v138
	v_cndmask_b32_e32 v53, v53, v169, vcc
	v_cmp_gt_i32_e32 vcc, v139, v128
	v_cmp_lt_i32_e64 s[0:1], v139, v137
	s_or_b64 vcc, vcc, s[0:1]
	v_add_u32_e32 v139, 41, v138
	v_cndmask_b32_e32 v54, v54, v169, vcc
	v_cmp_gt_i32_e32 vcc, v139, v128
	v_cmp_lt_i32_e64 s[0:1], v139, v137
	s_or_b64 vcc, vcc, s[0:1]
	v_add_u32_e32 v139, 42, v138
	v_cndmask_b32_e32 v55, v55, v169, vcc
	v_cmp_gt_i32_e32 vcc, v139, v128
	v_cmp_lt_i32_e64 s[0:1], v139, v137
	s_or_b64 vcc, vcc, s[0:1]
	v_add_u32_e32 v139, 43, v138
	v_cndmask_b32_e32 v56, v56, v169, vcc
	v_cmp_gt_i32_e32 vcc, v139, v128
	v_cmp_lt_i32_e64 s[0:1], v139, v137
	s_or_b64 vcc, vcc, s[0:1]
	v_add_u32_e32 v139, 48, v138
	v_cndmask_b32_e32 v57, v57, v169, vcc
	v_cmp_gt_i32_e32 vcc, v139, v128
	v_cmp_lt_i32_e64 s[0:1], v139, v137
	s_or_b64 vcc, vcc, s[0:1]
	v_add_u32_e32 v139, 49, v138
	v_cndmask_b32_e32 v58, v58, v169, vcc
	v_cmp_gt_i32_e32 vcc, v139, v128
	v_cmp_lt_i32_e64 s[0:1], v139, v137
	s_or_b64 vcc, vcc, s[0:1]
	v_add_u32_e32 v139, 50, v138
	v_cndmask_b32_e32 v59, v59, v169, vcc
	v_cmp_gt_i32_e32 vcc, v139, v128
	v_cmp_lt_i32_e64 s[0:1], v139, v137
	s_or_b64 vcc, vcc, s[0:1]
	v_add_u32_e32 v139, 51, v138
	v_cndmask_b32_e32 v60, v60, v169, vcc
	v_cmp_gt_i32_e32 vcc, v139, v128
	v_cmp_lt_i32_e64 s[0:1], v139, v137
	s_or_b64 vcc, vcc, s[0:1]
	v_add_u32_e32 v139, 56, v138
	v_cndmask_b32_e32 v61, v61, v169, vcc
	v_cmp_gt_i32_e32 vcc, v139, v128
	v_cmp_lt_i32_e64 s[0:1], v139, v137
	s_or_b64 vcc, vcc, s[0:1]
	v_add_u32_e32 v139, 57, v138
	v_cndmask_b32_e32 v62, v62, v169, vcc
	v_cmp_gt_i32_e32 vcc, v139, v128
	v_cmp_lt_i32_e64 s[0:1], v139, v137
	s_or_b64 vcc, vcc, s[0:1]
	v_add_u32_e32 v139, 58, v138
	v_cndmask_b32_e32 v63, v63, v169, vcc
	v_cmp_gt_i32_e32 vcc, v139, v128
	v_cmp_lt_i32_e64 s[0:1], v139, v137
	s_or_b64 vcc, vcc, s[0:1]
	v_add_u32_e32 v138, 59, v138
	v_cndmask_b32_e32 v64, v64, v169, vcc
	v_cmp_gt_i32_e32 vcc, v138, v128
	v_cmp_lt_i32_e64 s[0:1], v138, v137
	s_or_b64 s[22:23], vcc, s[0:1]
	s_and_saveexec_b64 s[0:1], s[22:23]
	v_mov_b32_e32 v65, 0xf149f2ca
	s_or_b64 exec, exec, s[0:1]
